# scan recurrence: H tile stored group-major so two time steps go out in one ds_write2_b32 (16 fewer LDS writes per chunk)
# baseline (speedup 1.0000x reference)
.LBB0_615:
	s_waitcnt vmcnt(0)
	v_cvt_pk_bf16_f32 v87, v87, v92
	v_cvt_pk_bf16_f32 v92, v89, v90
	v_cvt_pk_bf16_f32 v89, v131, v150
	v_mul_f32_e32 v131, v100, v100
	v_cvt_pk_bf16_f32 v88, v88, v149
	v_fmamk_f32 v149, v131, 0xb94c1982, v180
	v_fmaak_f32 v149, v131, v149, 0xbe2aaa9d
	v_mul_f32_e32 v149, v131, v149
	v_fmac_f32_e32 v100, v100, v149
	v_fmamk_f32 v149, v131, 0x37d75334, v181
	v_fmaak_f32 v149, v131, v149, 0x3d2aabf7
	v_fmaak_f32 v149, v131, v149, 0xbf000004
	v_lshlrev_b32_e32 v150, 30, v115
	v_and_b32_e32 v115, 1, v115
	v_fma_f32 v149, v131, v149, 1.0
	v_cmp_eq_u32_e64 s[46:47], 0, v115
	v_mul_f32_e32 v65, v65, v110
	v_xor_b32_e32 v107, v107, v106
	v_cndmask_b32_e64 v115, v149, v100, s[46:47]
	v_mul_f32_e32 v65, 0x3fb8aa3b, v65
	v_xor_b32_e32 v107, v107, v115
	v_exp_f32_e32 v115, v65
	v_and_b32_e32 v131, 0x80000000, v150
	v_xor_b32_e32 v107, v107, v131
	v_cmp_class_f32_e64 s[48:49], v106, s10
	v_cvt_pk_bf16_f32 v82, v82, v151
	v_xor_b32_e32 v147, v147, v146
	v_cndmask_b32_e64 v106, v191, v107, s[48:49]
	v_mul_f32_e32 v131, v115, v106
	v_mul_f32_e32 v106, v110, v104
	v_mul_f32_e32 v106, 0x3fb8aa3b, v106
	v_exp_f32_e32 v107, v106
	v_mul_f32_e32 v106, v128, v128
	v_fmamk_f32 v151, v106, 0xb94c1982, v180
	v_fmaak_f32 v151, v106, v151, 0xbe2aaa9d
	v_mul_f32_e32 v151, v106, v151
	v_fmac_f32_e32 v128, v128, v151
	v_fmamk_f32 v151, v106, 0x37d75334, v181
	v_fmaak_f32 v151, v106, v151, 0x3d2aabf7
	v_fmaak_f32 v151, v106, v151, 0xbf000004
	v_fma_f32 v106, v106, v151, 1.0
	v_lshlrev_b32_e32 v151, 30, v148
	v_and_b32_e32 v148, 1, v148
	v_cmp_eq_u32_e32 vcc, 0, v148
	v_cvt_pk_bf16_f32 v83, v83, v152
	v_and_b32_e32 v152, 0x80000000, v151
	v_cndmask_b32_e32 v148, v106, v128, vcc
	v_xor_b32_e32 v128, 0x80000000, v128
	v_xor_b32_e32 v147, v147, v148
	v_cndmask_b32_e32 v106, v128, v106, vcc
	v_xor_b32_e32 v147, v147, v152
	v_bitop3_b32 v106, v106, v151, s14 bitop3:0x78
	v_cmp_class_f32_e64 vcc, v146, s10
	v_cvt_pk_bf16_f32 v64, v64, v198
	v_cvt_pk_bf16_f32 v63, v195, v197
	v_cndmask_b32_e32 v106, v191, v106, vcc
	v_cndmask_b32_e32 v128, v191, v147, vcc
	v_pk_mul_f32 v[146:147], v[104:105], v[104:105]
	v_fma_f32 v106, v107, v106, -1.0
	v_mul_f32_e32 v107, v107, v128
	v_add_f32_e32 v128, v146, v147
	v_div_scale_f32 v146, s[96:97], v128, v128, 1.0
	v_rcp_f32_e32 v147, v146
	v_cvt_pk_bf16_f32 v62, v194, v196
	v_cvt_pk_bf16_f32 v68, v68, v175
	v_cvt_pk_bf16_f32 v67, v67, v173
	v_fma_f32 v148, -v146, v147, 1.0
	v_fmac_f32_e32 v147, v148, v147
	v_div_scale_f32 v148, vcc, 1.0, v128, 1.0
	v_mul_f32_e32 v151, v148, v147
	v_fma_f32 v152, -v146, v151, v148
	v_fmac_f32_e32 v151, v152, v147
	v_fma_f32 v146, -v146, v151, v148
	v_div_fmas_f32 v146, v146, v147, v151
	v_div_fixup_f32 v148, v146, v128, 1.0
	v_pk_mul_f32 v[146:147], v[104:105], v[106:107]
	v_cvt_pk_bf16_f32 v66, v66, v171
	v_add_f32_e32 v128, v146, v147
	v_mov_b32_e32 v146, v107
	v_mov_b32_e32 v147, v106
	v_pk_mul_f32 v[104:105], v[104:105], v[146:147]
	v_mul_f32_e32 v128, v148, v128
	v_sub_f32_e32 v104, v104, v105
	v_mul_f32_e32 v104, v148, v104
	v_pk_mul_f32 v[106:107], v[94:95], v[128:129] op_sel_hi:[1,0]
	v_pk_mul_f32 v[94:95], v[94:95], v[104:105] op_sel_hi:[1,0]
	v_pk_fma_f32 v[106:107], v[56:57], v[104:105], v[106:107] op_sel_hi:[1,0,1]
	v_pk_fma_f32 v[56:57], v[56:57], v[128:129], v[94:95] op_sel_hi:[1,0,1] neg_lo:[0,0,1] neg_hi:[0,0,1]
	v_cvt_pk_bf16_f32 v72, v72, v170
	v_mov_b32_e32 v57, v107
	v_mov_b32_e32 v56, v106
	v_cvt_pk_bf16_f32 v94, v56, v57
	v_pk_mul_f32 v[56:57], v[96:97], v[128:129] op_sel_hi:[1,0]
	v_pk_mul_f32 v[96:97], v[96:97], v[104:105] op_sel_hi:[1,0]
	v_pk_fma_f32 v[56:57], v[58:59], v[104:105], v[56:57] op_sel_hi:[1,0,1]
	v_pk_fma_f32 v[58:59], v[58:59], v[128:129], v[96:97] op_sel_hi:[1,0,1] neg_lo:[0,0,1] neg_hi:[0,0,1]
	v_cvt_pk_bf16_f32 v71, v71, v168
	s_nop 0
	s_nop 0
	v_cvt_pk_bf16_f32 v95, v56, v57
	v_pk_mul_f32 v[56:57], v[52:53], v[128:129] op_sel_hi:[1,0]
	v_pk_mul_f32 v[52:53], v[52:53], v[104:105] op_sel_hi:[1,0]
	v_pk_fma_f32 v[56:57], v[48:49], v[104:105], v[56:57] op_sel_hi:[1,0,1]
	v_pk_fma_f32 v[48:49], v[48:49], v[128:129], v[52:53] op_sel_hi:[1,0,1] neg_lo:[0,0,1] neg_hi:[0,0,1]
	v_pk_mul_f32 v[52:53], v[104:105], v[54:55] op_sel_hi:[0,1]
	v_mov_b32_e32 v49, v57
	v_mov_b32_e32 v48, v56
	v_cvt_pk_bf16_f32 v96, v48, v49
	v_pk_mul_f32 v[48:49], v[128:129], v[54:55] op_sel_hi:[0,1]
	v_pk_fma_f32 v[48:49], v[50:51], v[104:105], v[48:49] op_sel_hi:[1,0,1]
	v_pk_fma_f32 v[50:51], v[50:51], v[128:129], v[52:53] op_sel_hi:[1,0,1] neg_lo:[0,0,1] neg_hi:[0,0,1]
	v_and_b32_e32 v52, 1, v145
	s_nop 0
	s_nop 0
	v_cvt_pk_bf16_f32 v97, v48, v49
	v_mul_f32_e32 v48, v110, v102
	v_mul_f32_e32 v48, 0x3fb8aa3b, v48
	v_exp_f32_e32 v49, v48
	v_mul_f32_e32 v48, v144, v144
	v_fmamk_f32 v50, v48, 0xb94c1982, v180
	v_fmaak_f32 v50, v48, v50, 0xbe2aaa9d
	v_mul_f32_e32 v50, v48, v50
	v_fmac_f32_e32 v144, v144, v50
	v_fmamk_f32 v50, v48, 0x37d75334, v181
	v_fmaak_f32 v50, v48, v50, 0x3d2aabf7
	v_fmaak_f32 v50, v48, v50, 0xbf000004
	v_fma_f32 v48, v48, v50, 1.0
	v_cmp_eq_u32_e32 vcc, 0, v52
	v_lshlrev_b32_e32 v50, 30, v145
	v_xor_b32_e32 v53, v143, v142
	v_cndmask_b32_e32 v52, v48, v144, vcc
	v_and_b32_e32 v51, 0x80000000, v50
	v_xor_b32_e32 v52, v53, v52
	v_xor_b32_e32 v51, v52, v51
	v_xor_b32_e32 v52, 0x80000000, v144
	v_cndmask_b32_e32 v48, v52, v48, vcc
	v_bitop3_b32 v48, v48, v50, s14 bitop3:0x78
	v_cmp_class_f32_e64 vcc, v142, s10
	v_cvt_pk_bf16_f32 v70, v70, v166
	v_cvt_pk_bf16_f32 v76, v76, v165
	v_cndmask_b32_e32 v48, v191, v48, vcc
	v_cndmask_b32_e32 v50, v191, v51, vcc
	v_fma_f32 v48, v49, v48, -1.0
	v_mul_f32_e32 v49, v49, v50
	v_pk_mul_f32 v[50:51], v[102:103], v[102:103]
	v_cvt_pk_bf16_f32 v75, v75, v163
	v_add_f32_e32 v50, v50, v51
	v_div_scale_f32 v51, s[96:97], v50, v50, 1.0
	v_rcp_f32_e32 v52, v51
	v_cvt_pk_bf16_f32 v74, v74, v161
	v_cvt_pk_bf16_f32 v80, v80, v159
	v_cvt_pk_bf16_f32 v79, v79, v157
	v_fma_f32 v53, -v51, v52, 1.0
	v_fmac_f32_e32 v52, v53, v52
	v_div_scale_f32 v53, vcc, 1.0, v50, 1.0
	v_mul_f32_e32 v54, v53, v52
	v_fma_f32 v55, -v51, v54, v53
	v_fmac_f32_e32 v54, v55, v52
	v_fma_f32 v51, -v51, v54, v53
	v_div_fmas_f32 v51, v51, v52, v54
	v_mov_b32_e32 v52, v49
	v_mov_b32_e32 v53, v48
	v_div_fixup_f32 v54, v51, v50, 1.0
	v_pk_mul_f32 v[50:51], v[102:103], v[48:49]
	v_pk_mul_f32 v[48:49], v[102:103], v[52:53]
	v_add_f32_e32 v50, v50, v51
	v_sub_f32_e32 v48, v48, v49
	v_mul_f32_e32 v50, v54, v50
	v_mul_f32_e32 v48, v54, v48
	v_pk_mul_f32 v[52:53], v[44:45], v[50:51] op_sel_hi:[1,0]
	v_pk_mul_f32 v[44:45], v[44:45], v[48:49] op_sel_hi:[1,0]
	v_pk_fma_f32 v[52:53], v[40:41], v[48:49], v[52:53] op_sel_hi:[1,0,1]
	v_pk_fma_f32 v[40:41], v[40:41], v[50:51], v[44:45] op_sel_hi:[1,0,1] neg_lo:[0,0,1] neg_hi:[0,0,1]
	v_pk_mul_f32 v[44:45], v[46:47], v[48:49] op_sel_hi:[1,0]
	s_nop 0
	s_nop 0
	v_cvt_pk_bf16_f32 v102, v40, v41
	v_pk_mul_f32 v[40:41], v[46:47], v[50:51] op_sel_hi:[1,0]
	v_cvt_pk_bf16_f32 v78, v78, v156
	v_pk_fma_f32 v[40:41], v[42:43], v[48:49], v[40:41] op_sel_hi:[1,0,1]
	v_pk_fma_f32 v[42:43], v[42:43], v[50:51], v[44:45] op_sel_hi:[1,0,1] neg_lo:[0,0,1] neg_hi:[0,0,1]
	v_cvt_pk_bf16_f32 v84, v84, v154
	v_mov_b32_e32 v41, v43
	v_mov_b32_e32 v40, v42
	v_cvt_pk_bf16_f32 v103, v40, v41
	v_pk_mul_f32 v[40:41], v[36:37], v[50:51] op_sel_hi:[1,0]
	v_pk_mul_f32 v[36:37], v[36:37], v[48:49] op_sel_hi:[1,0]
	v_pk_fma_f32 v[40:41], v[32:33], v[48:49], v[40:41] op_sel_hi:[1,0,1]
	v_pk_fma_f32 v[32:33], v[32:33], v[50:51], v[36:37] op_sel_hi:[1,0,1] neg_lo:[0,0,1] neg_hi:[0,0,1]
	v_pk_mul_f32 v[36:37], v[48:49], v[38:39] op_sel_hi:[0,1]
	s_nop 0
	s_nop 0
	v_cvt_pk_bf16_f32 v104, v32, v33
	v_pk_mul_f32 v[32:33], v[50:51], v[38:39] op_sel_hi:[0,1]
	v_pk_fma_f32 v[32:33], v[34:35], v[48:49], v[32:33] op_sel_hi:[1,0,1]
	v_pk_fma_f32 v[34:35], v[34:35], v[50:51], v[36:37] op_sel_hi:[1,0,1] neg_lo:[0,0,1] neg_hi:[0,0,1]
	v_and_b32_e32 v36, 1, v117
	v_mov_b32_e32 v33, v35
	v_mov_b32_e32 v32, v34
	v_cvt_pk_bf16_f32 v105, v32, v33
	v_mul_f32_e32 v32, v110, v98
	v_mul_f32_e32 v32, 0x3fb8aa3b, v32
	v_exp_f32_e32 v33, v32
	v_mul_f32_e32 v32, v116, v116
	v_fmamk_f32 v34, v32, 0xb94c1982, v180
	v_fmaak_f32 v34, v32, v34, 0xbe2aaa9d
	v_mul_f32_e32 v34, v32, v34
	v_fmac_f32_e32 v116, v116, v34
	v_fmamk_f32 v34, v32, 0x37d75334, v181
	v_fmaak_f32 v34, v32, v34, 0x3d2aabf7
	v_fmaak_f32 v34, v32, v34, 0xbf000004
	v_fma_f32 v32, v32, v34, 1.0
	v_cmp_eq_u32_e32 vcc, 0, v36
	v_lshlrev_b32_e32 v34, 30, v117
	v_xor_b32_e32 v37, v109, v108
	v_cndmask_b32_e32 v36, v32, v116, vcc
	v_and_b32_e32 v35, 0x80000000, v34
	v_xor_b32_e32 v36, v37, v36
	v_xor_b32_e32 v35, v36, v35
	v_xor_b32_e32 v36, 0x80000000, v116
	v_cndmask_b32_e32 v32, v36, v32, vcc
	v_bitop3_b32 v32, v32, v34, s14 bitop3:0x78
	v_cmp_class_f32_e64 vcc, v108, s10
	v_cvt_pk_bf16_f32 v86, v86, v91
	v_cvt_pk_bf16_f32 v91, v69, v81
	v_cndmask_b32_e32 v32, v191, v32, vcc
	v_cndmask_b32_e32 v34, v191, v35, vcc
	v_fma_f32 v32, v33, v32, -1.0
	v_mul_f32_e32 v33, v33, v34
	v_pk_mul_f32 v[34:35], v[98:99], v[98:99]
	v_cvt_pk_bf16_f32 v90, v73, v77
	v_add_f32_e32 v34, v34, v35
	v_div_scale_f32 v35, s[96:97], v34, v34, 1.0
	v_rcp_f32_e32 v36, v35
	v_cvt_pk_bf16_f32 v93, v85, v93
	v_cvt_pk_bf16_f32 v85, v153, v155
	v_cvt_pk_bf16_f32 v81, v158, v160
	v_fma_f32 v37, -v35, v36, 1.0
	v_fmac_f32_e32 v36, v37, v36
	v_div_scale_f32 v37, vcc, 1.0, v34, 1.0
	v_mul_f32_e32 v38, v37, v36
	v_fma_f32 v39, -v35, v38, v37
	v_fmac_f32_e32 v38, v39, v36
	v_fma_f32 v35, -v35, v38, v37
	v_div_fmas_f32 v35, v35, v36, v38
	v_mov_b32_e32 v36, v33
	v_mov_b32_e32 v37, v32
	v_div_fixup_f32 v38, v35, v34, 1.0
	v_pk_mul_f32 v[34:35], v[98:99], v[32:33]
	v_pk_mul_f32 v[32:33], v[98:99], v[36:37]
	v_add_f32_e32 v34, v34, v35
	v_sub_f32_e32 v32, v32, v33
	v_mul_f32_e32 v34, v38, v34
	v_mul_f32_e32 v32, v38, v32
	v_pk_mul_f32 v[36:37], v[28:29], v[34:35] op_sel_hi:[1,0]
	v_pk_mul_f32 v[28:29], v[28:29], v[32:33] op_sel_hi:[1,0]
	v_pk_fma_f32 v[36:37], v[24:25], v[32:33], v[36:37] op_sel_hi:[1,0,1]
	v_pk_fma_f32 v[24:25], v[24:25], v[34:35], v[28:29] op_sel_hi:[1,0,1] neg_lo:[0,0,1] neg_hi:[0,0,1]
	v_pk_mul_f32 v[28:29], v[30:31], v[32:33] op_sel_hi:[1,0]
	v_mov_b32_e32 v25, v37
	v_mov_b32_e32 v24, v36
	v_cvt_pk_bf16_f32 v106, v24, v25
	v_pk_mul_f32 v[24:25], v[30:31], v[34:35] op_sel_hi:[1,0]
	v_cvt_pk_bf16_f32 v77, v162, v164
	v_pk_fma_f32 v[24:25], v[26:27], v[32:33], v[24:25] op_sel_hi:[1,0,1]
	v_pk_fma_f32 v[26:27], v[26:27], v[34:35], v[28:29] op_sel_hi:[1,0,1] neg_lo:[0,0,1] neg_hi:[0,0,1]
	v_cvt_pk_bf16_f32 v73, v167, v169
	s_nop 0
	s_nop 0
	v_cvt_pk_bf16_f32 v107, v24, v25
	v_pk_mul_f32 v[24:25], v[20:21], v[34:35] op_sel_hi:[1,0]
	v_pk_mul_f32 v[20:21], v[20:21], v[32:33] op_sel_hi:[1,0]
	v_pk_fma_f32 v[24:25], v[16:17], v[32:33], v[24:25] op_sel_hi:[1,0,1]
	v_pk_fma_f32 v[16:17], v[16:17], v[34:35], v[20:21] op_sel_hi:[1,0,1] neg_lo:[0,0,1] neg_hi:[0,0,1]
	v_pk_mul_f32 v[20:21], v[32:33], v[22:23] op_sel_hi:[0,1]
	v_mov_b32_e32 v17, v25
	v_mov_b32_e32 v16, v24
	v_cvt_pk_bf16_f32 v108, v16, v17
	v_pk_mul_f32 v[16:17], v[34:35], v[22:23] op_sel_hi:[0,1]
	v_pk_fma_f32 v[16:17], v[18:19], v[32:33], v[16:17] op_sel_hi:[1,0,1]
	v_pk_fma_f32 v[18:19], v[18:19], v[34:35], v[20:21] op_sel_hi:[1,0,1] neg_lo:[0,0,1] neg_hi:[0,0,1]
	v_and_b32_e32 v20, 1, v114
	s_nop 0
	s_nop 0
	v_cvt_pk_bf16_f32 v109, v16, v17
	v_mul_f32_e32 v16, v110, v60
	v_mul_f32_e32 v16, 0x3fb8aa3b, v16
	v_exp_f32_e32 v17, v16
	v_mul_f32_e32 v16, v113, v113
	v_fmamk_f32 v18, v16, 0xb94c1982, v180
	v_fmaak_f32 v18, v16, v18, 0xbe2aaa9d
	v_mul_f32_e32 v18, v16, v18
	v_fmac_f32_e32 v113, v113, v18
	v_fmamk_f32 v18, v16, 0x37d75334, v181
	v_fmaak_f32 v18, v16, v18, 0x3d2aabf7
	v_fmaak_f32 v18, v16, v18, 0xbf000004
	v_fma_f32 v16, v16, v18, 1.0
	v_cmp_eq_u32_e32 vcc, 0, v20
	v_lshlrev_b32_e32 v18, 30, v114
	v_xor_b32_e32 v21, v112, v111
	v_cndmask_b32_e32 v20, v16, v113, vcc
	v_and_b32_e32 v19, 0x80000000, v18
	v_xor_b32_e32 v20, v21, v20
	v_xor_b32_e32 v19, v20, v19
	v_xor_b32_e32 v20, 0x80000000, v113
	v_cndmask_b32_e32 v16, v20, v16, vcc
	v_bitop3_b32 v16, v16, v18, s14 bitop3:0x78
	v_cmp_class_f32_e64 vcc, v111, s10
	v_cvt_pk_bf16_f32 v69, v172, v174
	v_cvt_pk_bf16_f32 v65, v192, v193
	v_cndmask_b32_e32 v16, v191, v16, vcc
	v_cndmask_b32_e32 v18, v191, v19, vcc
	v_fma_f32 v16, v17, v16, -1.0
	v_mul_f32_e32 v17, v17, v18
	v_pk_mul_f32 v[18:19], v[60:61], v[60:61]
	s_nop 0
	v_add_f32_e32 v18, v18, v19
	v_div_scale_f32 v19, s[96:97], v18, v18, 1.0
	v_rcp_f32_e32 v20, v19
	s_nop 0
	v_fma_f32 v21, -v19, v20, 1.0
	v_fmac_f32_e32 v20, v21, v20
	v_div_scale_f32 v21, vcc, 1.0, v18, 1.0
	v_mul_f32_e32 v22, v21, v20
	v_fma_f32 v23, -v19, v22, v21
	v_fmac_f32_e32 v22, v23, v20
	v_fma_f32 v19, -v19, v22, v21
	v_div_fmas_f32 v19, v19, v20, v22
	v_mov_b32_e32 v20, v17
	v_mov_b32_e32 v21, v16
	v_div_fixup_f32 v22, v19, v18, 1.0
	v_pk_mul_f32 v[18:19], v[60:61], v[16:17]
	v_pk_mul_f32 v[16:17], v[60:61], v[20:21]
	v_add_f32_e32 v18, v18, v19
	v_sub_f32_e32 v16, v16, v17
	v_mul_f32_e32 v18, v22, v18
	v_mul_f32_e32 v16, v22, v16
	v_pk_mul_f32 v[20:21], v[12:13], v[18:19] op_sel_hi:[1,0]
	v_pk_mul_f32 v[12:13], v[12:13], v[16:17] op_sel_hi:[1,0]
	v_pk_fma_f32 v[20:21], v[8:9], v[16:17], v[20:21] op_sel_hi:[1,0,1]
	v_pk_fma_f32 v[8:9], v[8:9], v[18:19], v[12:13] op_sel_hi:[1,0,1] neg_lo:[0,0,1] neg_hi:[0,0,1]
	v_pk_mul_f32 v[12:13], v[14:15], v[16:17] op_sel_hi:[1,0]
	s_nop 0
	s_nop 0
	v_cvt_pk_bf16_f32 v110, v8, v9
	v_pk_mul_f32 v[8:9], v[14:15], v[18:19] op_sel_hi:[1,0]
	v_lshlrev_b32_e32 v60, 4, v140
	v_pk_fma_f32 v[8:9], v[10:11], v[16:17], v[8:9] op_sel_hi:[1,0,1]
	v_pk_fma_f32 v[10:11], v[10:11], v[18:19], v[12:13] op_sel_hi:[1,0,1] neg_lo:[0,0,1] neg_hi:[0,0,1]
	v_ashrrev_i32_e32 v61, 31, v60
	v_mov_b32_e32 v9, v11
	v_mov_b32_e32 v8, v10
	v_cvt_pk_bf16_f32 v111, v8, v9
	v_pk_mul_f32 v[8:9], v[4:5], v[18:19] op_sel_hi:[1,0]
	v_pk_mul_f32 v[4:5], v[4:5], v[16:17] op_sel_hi:[1,0]
	v_pk_fma_f32 v[8:9], v[0:1], v[16:17], v[8:9] op_sel_hi:[1,0,1]
	v_pk_fma_f32 v[0:1], v[0:1], v[18:19], v[4:5] op_sel_hi:[1,0,1] neg_lo:[0,0,1] neg_hi:[0,0,1]
	v_pk_mul_f32 v[4:5], v[16:17], v[6:7] op_sel_hi:[0,1]
	s_nop 0
	s_nop 0
	v_cvt_pk_bf16_f32 v112, v0, v1
	v_pk_mul_f32 v[0:1], v[18:19], v[6:7] op_sel_hi:[0,1]
	v_pk_fma_f32 v[0:1], v[2:3], v[16:17], v[0:1] op_sel_hi:[1,0,1]
	v_pk_fma_f32 v[2:3], v[2:3], v[18:19], v[4:5] op_sel_hi:[1,0,1] neg_lo:[0,0,1] neg_hi:[0,0,1]
	s_nop 0
	v_mov_b32_e32 v1, v3
	v_mov_b32_e32 v0, v2
	v_cvt_pk_bf16_f32 v113, v0, v1
	v_xor_b32_e32 v0, 0x80000000, v100
	v_cndmask_b32_e64 v0, v0, v149, s[46:47]
	v_bitop3_b32 v0, v0, v150, s14 bitop3:0x78
	s_lshl_b32 s46, s50, 12
	v_cndmask_b32_e64 v0, v191, v0, s[48:49]
	s_add_i32 s48, s46, 0x2000
	s_lshl_b32 s49, s50, 8
	s_and_b64 s[46:47], s[76:77], exec
	s_cselect_b32 s51, s48, s49
	s_cmp_eq_u32 s38, 0
	s_cselect_b64 s[46:47], -1, 0
	s_and_b64 vcc, s[46:47], exec
	s_mov_b32 s46, 0x27600000
	s_cselect_b32 s46, s46, 0x2c600000
	s_add_u32 s46, s58, s46
	v_mul_f32_e32 v150, v115, v0
	s_addc_u32 s47, s59, 0
	s_mov_b64 s[48:49], -1
	s_cbranch_vccnz .LBB0_622
	v_and_b32_e32 v56, 31, v133
	v_bfe_u32 v57, v133, 5, 1
	v_and_b32_e32 v58, 63, v133
	v_lshrrev_b32_e32 v59, 2, v58
	v_mul_u32_u24_e32 v59, 0x210, v59
	v_and_b32_e32 v240, 3, v58
	v_lshl_add_u32 v240, v240, 2, v59
	v_add_u32_e32 v240, v240, v127
	v_add_u32_e32 v240, 0x2000, v240
	v_mul_u32_u24_e32 v59, 0x210, v57
	v_lshl_add_u32 v241, v56, 4, v59
	v_add_u32_e32 v241, v241, v127
	s_lshl_b32 s76, s39, 5
	s_add_i32 s76, s76, s51
	s_sub_i32 s76, s76, 32
	v_add_u32_e32 v242, s76, v56
	s_mov_b32 s48, 0xffff0000
	s_mov_b32 s49, -1
	v_mov_b32_e32 v243, 0
	v_lshlrev_b64 v[242:243], 11, v[242:243]
	v_lshlrev_b64 v[248:249], 1, v[60:61]
	v_lshl_add_u64 v[244:245], s[94:95], 0, v[242:243]
	v_lshl_add_u64 v[246:247], s[46:47], 0, v[242:243]
	v_lshl_add_u64 v[244:245], v[244:245], 0, v[248:249]
	v_lshl_add_u64 v[246:247], v[246:247], 0, v[248:249]
	v_lshlrev_b32_e32 v128, 4, v57
	v_lshl_add_u64 v[244:245], v[244:245], 0, v[128:129]
	v_lshlrev_b32_e32 v128, 3, v57
	v_lshl_add_u64 v[246:247], v[246:247], 0, v[128:129]
	global_load_dwordx4 v[48:51], v[244:245], off
	s_mov_b32 s77, 1
	s_mov_b32 s76, 0
	s_cmp_lt_u32 s77, s39
	s_cselect_b32 s46, s48, 0
	s_cselect_b32 s47, s49, 0
	s_add_i32 s77, s77, 1
	v_lshl_add_u64 v[244:245], v[244:245], 0, s[46:47]
	global_load_dwordx4 v[52:55], v[244:245], off
	v_mov_b32_e32 v174, v135
	v_mov_b32_e32 v252, v150
	v_mov_b32_e32 v175, v101
	s_waitcnt vmcnt(0)
	v_mfma_f32_32x32x16_bf16 v[0:15], v[48:51], v[110:113], 0
	v_mfma_f32_32x32x16_bf16 v[16:31], v[48:51], v[102:105], 0
	v_mfma_f32_32x32x16_bf16 v[32:47], v[48:51], v[106:109], 0
	v_mfma_f32_32x32x16_bf16 v[192:207], v[48:51], v[94:97], 0
	s_nop 15
	v_permlane32_swap_b32 v0, v16
	v_permlane32_swap_b32 v1, v17
	v_permlane32_swap_b32 v2, v18
	v_permlane32_swap_b32 v3, v19
	v_permlane32_swap_b32 v4, v20
	v_permlane32_swap_b32 v5, v21
	v_permlane32_swap_b32 v6, v22
	v_permlane32_swap_b32 v7, v23
	v_permlane32_swap_b32 v8, v24
	v_permlane32_swap_b32 v9, v25
	v_permlane32_swap_b32 v10, v26
	v_permlane32_swap_b32 v11, v27
	v_permlane32_swap_b32 v12, v28
	v_permlane32_swap_b32 v13, v29
	v_permlane32_swap_b32 v14, v30
	v_permlane32_swap_b32 v15, v31
	v_permlane32_swap_b32 v32, v192
	v_permlane32_swap_b32 v33, v193
	v_permlane32_swap_b32 v34, v194
	v_permlane32_swap_b32 v35, v195
	v_permlane32_swap_b32 v36, v196
	v_permlane32_swap_b32 v37, v197
	v_permlane32_swap_b32 v38, v198
	v_permlane32_swap_b32 v39, v199
	v_permlane32_swap_b32 v40, v200
	v_permlane32_swap_b32 v41, v201
	v_permlane32_swap_b32 v42, v202
	v_permlane32_swap_b32 v43, v203
	v_permlane32_swap_b32 v44, v204
	v_permlane32_swap_b32 v45, v205
	v_permlane32_swap_b32 v46, v206
	v_permlane32_swap_b32 v47, v207
	s_nop 1
.Lscr_loop:
	s_nop 1
	v_fma_f32 v31, -v131, v175, v31
	v_fma_f32 v207, v131, v174, v207
	v_fmac_f32_e32 v31, v252, v174
	v_fmac_f32_e32 v207, v252, v175
	v_cvt_pk_bf16_f32 v98, v31, v207
	v_fma_f32 v30, -v131, v207, v30
	v_fma_f32 v206, v131, v31, v206
	v_fmac_f32_e32 v30, v252, v31
	v_fmac_f32_e32 v206, v252, v207
	v_cvt_pk_bf16_f32 v99, v30, v206
	ds_write2_b32 v240, v98, v99 offset0:124 offset1:120
	v_fma_f32 v29, -v131, v206, v29
	v_fma_f32 v205, v131, v30, v205
	v_fmac_f32_e32 v29, v252, v30
	v_fmac_f32_e32 v205, v252, v206
	v_cvt_pk_bf16_f32 v100, v29, v205
	v_fma_f32 v28, -v131, v205, v28
	v_fma_f32 v204, v131, v29, v204
	v_fmac_f32_e32 v28, v252, v29
	v_fmac_f32_e32 v204, v252, v205
	v_cvt_pk_bf16_f32 v128, v28, v204
	ds_write2_b32 v240, v100, v128 offset0:116 offset1:112
	s_cmp_eq_u32 s76, 0
	s_cbranch_scc1 .Lscr_noy
	v_add_f32_e32 v242, v142, v158
	v_add_f32_e32 v243, v143, v159
	v_add_f32_e32 v60, v144, v160
	v_add_f32_e32 v61, v145, v161
	v_add_f32_e32 v116, v146, v162
	v_add_f32_e32 v117, v147, v163
	v_add_f32_e32 v100, v148, v164
	v_add_f32_e32 v128, v149, v165
	v_cvt_pk_bf16_f32 v242, v242, v243
	v_cvt_pk_bf16_f32 v243, v60, v61
	v_cvt_pk_bf16_f32 v60, v116, v117
	v_cvt_pk_bf16_f32 v61, v100, v128
	global_store_dwordx2 v[246:247], v[242:243], off
	global_store_dwordx2 v[246:247], v[60:61], off offset:16
	v_lshl_add_u64 v[246:247], v[246:247], 0, s[48:49]
.Lscr_noy:
	v_fma_f32 v15, -v131, v204, v15
	v_fma_f32 v47, v131, v28, v47
	v_fmac_f32_e32 v15, v252, v28
	v_fmac_f32_e32 v47, v252, v204
	v_cvt_pk_bf16_f32 v98, v15, v47
	v_fma_f32 v14, -v131, v47, v14
	v_fma_f32 v46, v131, v15, v46
	v_fmac_f32_e32 v14, v252, v15
	v_fmac_f32_e32 v46, v252, v47
	v_cvt_pk_bf16_f32 v99, v14, v46
	ds_write2_b32 v240, v98, v99 offset0:108 offset1:104
	v_fma_f32 v13, -v131, v46, v13
	v_fma_f32 v45, v131, v14, v45
	v_fmac_f32_e32 v13, v252, v14
	v_fmac_f32_e32 v45, v252, v46
	v_cvt_pk_bf16_f32 v100, v13, v45
	v_fma_f32 v12, -v131, v45, v12
	v_fma_f32 v44, v131, v13, v44
	v_fmac_f32_e32 v12, v252, v13
	v_fmac_f32_e32 v44, v252, v45
	v_cvt_pk_bf16_f32 v128, v12, v44
	ds_write2_b32 v240, v100, v128 offset0:100 offset1:96
	v_fma_f32 v27, -v131, v44, v27
	v_fma_f32 v203, v131, v12, v203
	v_fmac_f32_e32 v27, v252, v12
	v_fmac_f32_e32 v203, v252, v44
	v_cvt_pk_bf16_f32 v98, v27, v203
	v_fma_f32 v26, -v131, v203, v26
	v_fma_f32 v202, v131, v27, v202
	v_fmac_f32_e32 v26, v252, v27
	v_fmac_f32_e32 v202, v252, v203
	v_cvt_pk_bf16_f32 v99, v26, v202
	ds_write2_b32 v240, v98, v99 offset0:92 offset1:88
	v_fma_f32 v25, -v131, v202, v25
	v_fma_f32 v201, v131, v26, v201
	v_fmac_f32_e32 v25, v252, v26
	v_fmac_f32_e32 v201, v252, v202
	v_cvt_pk_bf16_f32 v100, v25, v201
	v_fma_f32 v24, -v131, v201, v24
	v_fma_f32 v200, v131, v25, v200
	v_fmac_f32_e32 v24, v252, v25
	v_fmac_f32_e32 v200, v252, v201
	v_cvt_pk_bf16_f32 v128, v24, v200
	ds_write2_b32 v240, v100, v128 offset0:84 offset1:80
	v_fma_f32 v11, -v131, v200, v11
	v_fma_f32 v43, v131, v24, v43
	v_fmac_f32_e32 v11, v252, v24
	v_fmac_f32_e32 v43, v252, v200
	v_cvt_pk_bf16_f32 v98, v11, v43
	v_fma_f32 v10, -v131, v43, v10
	v_fma_f32 v42, v131, v11, v42
	v_fmac_f32_e32 v10, v252, v11
	v_fmac_f32_e32 v42, v252, v43
	v_cvt_pk_bf16_f32 v99, v10, v42
	ds_write2_b32 v240, v98, v99 offset0:76 offset1:72
	v_fma_f32 v9, -v131, v42, v9
	v_fma_f32 v41, v131, v10, v41
	v_fmac_f32_e32 v9, v252, v10
	v_fmac_f32_e32 v41, v252, v42
	v_cvt_pk_bf16_f32 v100, v9, v41
	v_fma_f32 v8, -v131, v41, v8
	v_fma_f32 v40, v131, v9, v40
	v_fmac_f32_e32 v8, v252, v9
	v_fmac_f32_e32 v40, v252, v41
	v_cvt_pk_bf16_f32 v128, v8, v40
	ds_write2_b32 v240, v100, v128 offset0:68 offset1:64
	v_fma_f32 v23, -v131, v40, v23
	v_fma_f32 v199, v131, v8, v199
	v_fmac_f32_e32 v23, v252, v8
	v_fmac_f32_e32 v199, v252, v40
	v_cvt_pk_bf16_f32 v98, v23, v199
	v_fma_f32 v22, -v131, v199, v22
	v_fma_f32 v198, v131, v23, v198
	v_fmac_f32_e32 v22, v252, v23
	v_fmac_f32_e32 v198, v252, v199
	v_cvt_pk_bf16_f32 v99, v22, v198
	ds_write2_b32 v240, v98, v99 offset0:60 offset1:56
	v_fma_f32 v21, -v131, v198, v21
	v_fma_f32 v197, v131, v22, v197
	v_fmac_f32_e32 v21, v252, v22
	v_fmac_f32_e32 v197, v252, v198
	v_cvt_pk_bf16_f32 v100, v21, v197
	v_fma_f32 v20, -v131, v197, v20
	v_fma_f32 v196, v131, v21, v196
	v_fmac_f32_e32 v20, v252, v21
	v_fmac_f32_e32 v196, v252, v197
	v_cvt_pk_bf16_f32 v128, v20, v196
	ds_write2_b32 v240, v100, v128 offset0:52 offset1:48
	v_fma_f32 v7, -v131, v196, v7
	v_fma_f32 v39, v131, v20, v39
	v_fmac_f32_e32 v7, v252, v20
	v_fmac_f32_e32 v39, v252, v196
	v_cvt_pk_bf16_f32 v98, v7, v39
	v_fma_f32 v6, -v131, v39, v6
	v_fma_f32 v38, v131, v7, v38
	v_fmac_f32_e32 v6, v252, v7
	v_fmac_f32_e32 v38, v252, v39
	v_cvt_pk_bf16_f32 v99, v6, v38
	ds_write2_b32 v240, v98, v99 offset0:44 offset1:40
	v_fma_f32 v5, -v131, v38, v5
	v_fma_f32 v37, v131, v6, v37
	v_fmac_f32_e32 v5, v252, v6
	v_fmac_f32_e32 v37, v252, v38
	v_cvt_pk_bf16_f32 v100, v5, v37
	v_fma_f32 v4, -v131, v37, v4
	v_fma_f32 v36, v131, v5, v36
	v_fmac_f32_e32 v4, v252, v5
	v_fmac_f32_e32 v36, v252, v37
	v_cvt_pk_bf16_f32 v128, v4, v36
	ds_write2_b32 v240, v100, v128 offset0:36 offset1:32
	v_fma_f32 v19, -v131, v36, v19
	v_fma_f32 v195, v131, v4, v195
	v_fmac_f32_e32 v19, v252, v4
	v_fmac_f32_e32 v195, v252, v36
	v_cvt_pk_bf16_f32 v98, v19, v195
	v_fma_f32 v18, -v131, v195, v18
	v_fma_f32 v194, v131, v19, v194
	v_fmac_f32_e32 v18, v252, v19
	v_fmac_f32_e32 v194, v252, v195
	v_cvt_pk_bf16_f32 v99, v18, v194
	ds_write2_b32 v240, v98, v99 offset0:28 offset1:24
	v_fma_f32 v17, -v131, v194, v17
	v_fma_f32 v193, v131, v18, v193
	v_fmac_f32_e32 v17, v252, v18
	v_fmac_f32_e32 v193, v252, v194
	v_cvt_pk_bf16_f32 v100, v17, v193
	v_fma_f32 v16, -v131, v193, v16
	v_fma_f32 v192, v131, v17, v192
	v_fmac_f32_e32 v16, v252, v17
	v_fmac_f32_e32 v192, v252, v193
	v_cvt_pk_bf16_f32 v128, v16, v192
	ds_write2_b32 v240, v100, v128 offset0:20 offset1:16
	v_fma_f32 v3, -v131, v192, v3
	v_fma_f32 v35, v131, v16, v35
	v_fmac_f32_e32 v3, v252, v16
	v_fmac_f32_e32 v35, v252, v192
	v_cvt_pk_bf16_f32 v98, v3, v35
	v_fma_f32 v2, -v131, v35, v2
	v_fma_f32 v34, v131, v3, v34
	v_fmac_f32_e32 v2, v252, v3
	v_fmac_f32_e32 v34, v252, v35
	v_cvt_pk_bf16_f32 v99, v2, v34
	ds_write2_b32 v240, v98, v99 offset0:12 offset1:8
	v_fma_f32 v1, -v131, v34, v1
	v_fma_f32 v33, v131, v2, v33
	v_fmac_f32_e32 v1, v252, v2
	v_fmac_f32_e32 v33, v252, v34
	v_cvt_pk_bf16_f32 v100, v1, v33
	v_fma_f32 v174, -v131, v33, v0
	v_fma_f32 v175, v131, v1, v32
	v_fmac_f32_e32 v174, v252, v1
	v_fmac_f32_e32 v175, v252, v33
	v_cvt_pk_bf16_f32 v128, v174, v175
	ds_write2_b32 v240, v100, v128 offset0:4 offset1:0
	ds_read_b128 v[208:211], v241 offset:8192
	ds_read_b128 v[212:215], v241 offset:9248
	ds_read_b128 v[216:219], v241 offset:10304
	ds_read_b128 v[220:223], v241 offset:11360
	ds_read_b128 v[224:227], v241 offset:12416
	ds_read_b128 v[228:231], v241 offset:13472
	ds_read_b128 v[232:235], v241 offset:14528
	ds_read_b128 v[236:239], v241 offset:15584
	s_waitcnt vmcnt(2)
	v_mov_b64_e32 v[48:49], v[52:53]
	v_mov_b64_e32 v[50:51], v[54:55]
	s_cmp_lt_u32 s77, s39
	s_cselect_b32 s46, s48, 0
	s_cselect_b32 s47, s49, 0
	s_add_i32 s77, s77, 1
	v_lshl_add_u64 v[244:245], v[244:245], 0, s[46:47]
	global_load_dwordx4 v[52:55], v[244:245], off
	v_mfma_f32_32x32x16_bf16 v[0:15], v[48:51], v[110:113], 0
	v_mfma_f32_32x32x16_bf16 v[16:31], v[48:51], v[102:105], 0
	v_mfma_f32_32x32x16_bf16 v[32:47], v[48:51], v[106:109], 0
	v_mfma_f32_32x32x16_bf16 v[192:207], v[48:51], v[94:97], 0
	s_waitcnt lgkmcnt(7)
	v_mfma_f32_32x32x16_bf16 v[142:157], v[90:93], v[208:211], 0
	s_nop 6
	v_permlane32_swap_b32 v0, v16
	v_permlane32_swap_b32 v1, v17
	v_permlane32_swap_b32 v2, v18
	v_permlane32_swap_b32 v3, v19
	s_waitcnt lgkmcnt(6)
	v_mfma_f32_32x32x16_bf16 v[158:173], v[86:89], v[212:215], 0
	v_permlane32_swap_b32 v4, v20
	v_permlane32_swap_b32 v5, v21
	v_permlane32_swap_b32 v6, v22
	v_permlane32_swap_b32 v7, v23
	s_waitcnt lgkmcnt(5)
	v_mfma_f32_32x32x16_bf16 v[142:157], v[82:85], v[216:219], v[142:157]
	v_permlane32_swap_b32 v8, v24
	v_permlane32_swap_b32 v9, v25
	v_permlane32_swap_b32 v10, v26
	v_permlane32_swap_b32 v11, v27
	s_waitcnt lgkmcnt(4)
	v_mfma_f32_32x32x16_bf16 v[158:173], v[78:81], v[220:223], v[158:173]
	v_permlane32_swap_b32 v12, v28
	v_permlane32_swap_b32 v13, v29
	v_permlane32_swap_b32 v14, v30
	v_permlane32_swap_b32 v15, v31
	s_waitcnt lgkmcnt(3)
	v_mfma_f32_32x32x16_bf16 v[142:157], v[74:77], v[224:227], v[142:157]
	v_permlane32_swap_b32 v32, v192
	v_permlane32_swap_b32 v33, v193
	v_permlane32_swap_b32 v34, v194
	v_permlane32_swap_b32 v35, v195
	s_waitcnt lgkmcnt(2)
	v_mfma_f32_32x32x16_bf16 v[158:173], v[70:73], v[228:231], v[158:173]
	v_permlane32_swap_b32 v36, v196
	v_permlane32_swap_b32 v37, v197
	v_permlane32_swap_b32 v38, v198
	v_permlane32_swap_b32 v39, v199
	s_waitcnt lgkmcnt(1)
	v_mfma_f32_32x32x16_bf16 v[142:157], v[66:69], v[232:235], v[142:157]
	v_permlane32_swap_b32 v40, v200
	v_permlane32_swap_b32 v41, v201
	v_permlane32_swap_b32 v42, v202
	v_permlane32_swap_b32 v43, v203
	s_waitcnt lgkmcnt(0)
	v_mfma_f32_32x32x16_bf16 v[158:173], v[62:65], v[236:239], v[158:173]
	v_permlane32_swap_b32 v44, v204
	v_permlane32_swap_b32 v45, v205
	v_permlane32_swap_b32 v46, v206
	v_permlane32_swap_b32 v47, v207
	s_add_i32 s76, s76, 1
	s_cmp_lt_u32 s76, s39
	s_cbranch_scc1 .Lscr_loop
	s_nop 15
	v_add_f32_e32 v242, v142, v158
	v_add_f32_e32 v243, v143, v159
	v_add_f32_e32 v60, v144, v160
	v_add_f32_e32 v61, v145, v161
	v_add_f32_e32 v116, v146, v162
	v_add_f32_e32 v117, v147, v163
	v_add_f32_e32 v100, v148, v164
	v_add_f32_e32 v128, v149, v165
	v_cvt_pk_bf16_f32 v242, v242, v243
	v_cvt_pk_bf16_f32 v243, v60, v61
	v_cvt_pk_bf16_f32 v60, v116, v117
	v_cvt_pk_bf16_f32 v61, v100, v128
	global_store_dwordx2 v[246:247], v[242:243], off
	global_store_dwordx2 v[246:247], v[60:61], off offset:16
	v_lshl_add_u64 v[246:247], v[246:247], 0, s[48:49]
	v_mov_b32_e32 v114, v174
	v_mov_b32_e32 v115, v175
	s_branch .LBB0_629
.LBB0_622:
	s_and_b64 vcc, exec, s[48:49]
	s_cbranch_vccz .LBB0_630
	v_and_b32_e32 v56, 31, v133
	v_bfe_u32 v57, v133, 5, 1
	v_and_b32_e32 v58, 63, v133
	v_lshrrev_b32_e32 v59, 2, v58
	v_mul_u32_u24_e32 v59, 0x210, v59
	v_and_b32_e32 v240, 3, v58
	v_lshl_add_u32 v240, v240, 2, v59
	v_add_u32_e32 v240, v240, v127
	v_add_u32_e32 v240, 0x2000, v240
	v_mul_u32_u24_e32 v59, 0x210, v57
	v_lshl_add_u32 v241, v56, 4, v59
	v_add_u32_e32 v241, v241, v127
	v_add_u32_e32 v242, s51, v56
	s_mov_b32 s48, 0x10000
	s_mov_b32 s49, 0
	v_mov_b32_e32 v243, 0
	v_lshlrev_b64 v[242:243], 11, v[242:243]
	v_lshlrev_b64 v[248:249], 1, v[60:61]
	v_lshl_add_u64 v[244:245], s[94:95], 0, v[242:243]
	v_lshl_add_u64 v[246:247], s[46:47], 0, v[242:243]
	v_lshl_add_u64 v[244:245], v[244:245], 0, v[248:249]
	v_lshl_add_u64 v[246:247], v[246:247], 0, v[248:249]
	v_lshlrev_b32_e32 v128, 4, v57
	v_lshl_add_u64 v[244:245], v[244:245], 0, v[128:129]
	v_lshlrev_b32_e32 v128, 3, v57
	v_lshl_add_u64 v[246:247], v[246:247], 0, v[128:129]
	global_load_dwordx4 v[48:51], v[244:245], off
	s_mov_b32 s77, 1
	s_mov_b32 s76, 0
	s_cmp_lt_u32 s77, s39
	s_cselect_b32 s46, s48, 0
	s_cselect_b32 s47, s49, 0
	s_add_i32 s77, s77, 1
	v_lshl_add_u64 v[244:245], v[244:245], 0, s[46:47]
	global_load_dwordx4 v[52:55], v[244:245], off
	v_mov_b32_e32 v174, v135
	v_mov_b32_e32 v252, v150
	v_mov_b32_e32 v175, v101
	s_waitcnt vmcnt(0)
	v_mfma_f32_32x32x16_bf16 v[0:15], v[48:51], v[110:113], 0
	v_mfma_f32_32x32x16_bf16 v[16:31], v[48:51], v[102:105], 0
	v_mfma_f32_32x32x16_bf16 v[32:47], v[48:51], v[106:109], 0
	v_mfma_f32_32x32x16_bf16 v[192:207], v[48:51], v[94:97], 0
	s_nop 15
	v_permlane32_swap_b32 v0, v16
	v_permlane32_swap_b32 v1, v17
	v_permlane32_swap_b32 v2, v18
	v_permlane32_swap_b32 v3, v19
	v_permlane32_swap_b32 v4, v20
	v_permlane32_swap_b32 v5, v21
	v_permlane32_swap_b32 v6, v22
	v_permlane32_swap_b32 v7, v23
	v_permlane32_swap_b32 v8, v24
	v_permlane32_swap_b32 v9, v25
	v_permlane32_swap_b32 v10, v26
	v_permlane32_swap_b32 v11, v27
	v_permlane32_swap_b32 v12, v28
	v_permlane32_swap_b32 v13, v29
	v_permlane32_swap_b32 v14, v30
	v_permlane32_swap_b32 v15, v31
	v_permlane32_swap_b32 v32, v192
	v_permlane32_swap_b32 v33, v193
	v_permlane32_swap_b32 v34, v194
	v_permlane32_swap_b32 v35, v195
	v_permlane32_swap_b32 v36, v196
	v_permlane32_swap_b32 v37, v197
	v_permlane32_swap_b32 v38, v198
	v_permlane32_swap_b32 v39, v199
	v_permlane32_swap_b32 v40, v200
	v_permlane32_swap_b32 v41, v201
	v_permlane32_swap_b32 v42, v202
	v_permlane32_swap_b32 v43, v203
	v_permlane32_swap_b32 v44, v204
	v_permlane32_swap_b32 v45, v205
	v_permlane32_swap_b32 v46, v206
	v_permlane32_swap_b32 v47, v207
	s_nop 1
.Lscf_loop:
	s_nop 1
	v_fma_f32 v0, -v131, v175, v0
	v_fma_f32 v32, v131, v174, v32
	v_fmac_f32_e32 v0, v252, v174
	v_fmac_f32_e32 v32, v252, v175
	v_cvt_pk_bf16_f32 v98, v0, v32
	v_fma_f32 v1, -v131, v32, v1
	v_fma_f32 v33, v131, v0, v33
	v_fmac_f32_e32 v1, v252, v0
	v_fmac_f32_e32 v33, v252, v32
	v_cvt_pk_bf16_f32 v99, v1, v33
	ds_write2_b32 v240, v98, v99 offset0:0 offset1:4
	v_fma_f32 v2, -v131, v33, v2
	v_fma_f32 v34, v131, v1, v34
	v_fmac_f32_e32 v2, v252, v1
	v_fmac_f32_e32 v34, v252, v33
	v_cvt_pk_bf16_f32 v100, v2, v34
	v_fma_f32 v3, -v131, v34, v3
	v_fma_f32 v35, v131, v2, v35
	v_fmac_f32_e32 v3, v252, v2
	v_fmac_f32_e32 v35, v252, v34
	v_cvt_pk_bf16_f32 v128, v3, v35
	ds_write2_b32 v240, v100, v128 offset0:8 offset1:12
	s_cmp_eq_u32 s76, 0
	s_cbranch_scc1 .Lscf_noy
	v_add_f32_e32 v242, v142, v158
	v_add_f32_e32 v243, v143, v159
	v_add_f32_e32 v60, v144, v160
	v_add_f32_e32 v61, v145, v161
	v_add_f32_e32 v116, v146, v162
	v_add_f32_e32 v117, v147, v163
	v_add_f32_e32 v100, v148, v164
	v_add_f32_e32 v128, v149, v165
	v_cvt_pk_bf16_f32 v242, v242, v243
	v_cvt_pk_bf16_f32 v243, v60, v61
	v_cvt_pk_bf16_f32 v60, v116, v117
	v_cvt_pk_bf16_f32 v61, v100, v128
	global_store_dwordx2 v[246:247], v[242:243], off
	global_store_dwordx2 v[246:247], v[60:61], off offset:16
	v_lshl_add_u64 v[246:247], v[246:247], 0, s[48:49]
.Lscf_noy:
	v_fma_f32 v16, -v131, v35, v16
	v_fma_f32 v192, v131, v3, v192
	v_fmac_f32_e32 v16, v252, v3
	v_fmac_f32_e32 v192, v252, v35
	v_cvt_pk_bf16_f32 v98, v16, v192
	v_fma_f32 v17, -v131, v192, v17
	v_fma_f32 v193, v131, v16, v193
	v_fmac_f32_e32 v17, v252, v16
	v_fmac_f32_e32 v193, v252, v192
	v_cvt_pk_bf16_f32 v99, v17, v193
	ds_write2_b32 v240, v98, v99 offset0:16 offset1:20
	v_fma_f32 v18, -v131, v193, v18
	v_fma_f32 v194, v131, v17, v194
	v_fmac_f32_e32 v18, v252, v17
	v_fmac_f32_e32 v194, v252, v193
	v_cvt_pk_bf16_f32 v100, v18, v194
	v_fma_f32 v19, -v131, v194, v19
	v_fma_f32 v195, v131, v18, v195
	v_fmac_f32_e32 v19, v252, v18
	v_fmac_f32_e32 v195, v252, v194
	v_cvt_pk_bf16_f32 v128, v19, v195
	ds_write2_b32 v240, v100, v128 offset0:24 offset1:28
	v_fma_f32 v4, -v131, v195, v4
	v_fma_f32 v36, v131, v19, v36
	v_fmac_f32_e32 v4, v252, v19
	v_fmac_f32_e32 v36, v252, v195
	v_cvt_pk_bf16_f32 v98, v4, v36
	v_fma_f32 v5, -v131, v36, v5
	v_fma_f32 v37, v131, v4, v37
	v_fmac_f32_e32 v5, v252, v4
	v_fmac_f32_e32 v37, v252, v36
	v_cvt_pk_bf16_f32 v99, v5, v37
	ds_write2_b32 v240, v98, v99 offset0:32 offset1:36
	v_fma_f32 v6, -v131, v37, v6
	v_fma_f32 v38, v131, v5, v38
	v_fmac_f32_e32 v6, v252, v5
	v_fmac_f32_e32 v38, v252, v37
	v_cvt_pk_bf16_f32 v100, v6, v38
	v_fma_f32 v7, -v131, v38, v7
	v_fma_f32 v39, v131, v6, v39
	v_fmac_f32_e32 v7, v252, v6
	v_fmac_f32_e32 v39, v252, v38
	v_cvt_pk_bf16_f32 v128, v7, v39
	ds_write2_b32 v240, v100, v128 offset0:40 offset1:44
	v_fma_f32 v20, -v131, v39, v20
	v_fma_f32 v196, v131, v7, v196
	v_fmac_f32_e32 v20, v252, v7
	v_fmac_f32_e32 v196, v252, v39
	v_cvt_pk_bf16_f32 v98, v20, v196
	v_fma_f32 v21, -v131, v196, v21
	v_fma_f32 v197, v131, v20, v197
	v_fmac_f32_e32 v21, v252, v20
	v_fmac_f32_e32 v197, v252, v196
	v_cvt_pk_bf16_f32 v99, v21, v197
	ds_write2_b32 v240, v98, v99 offset0:48 offset1:52
	v_fma_f32 v22, -v131, v197, v22
	v_fma_f32 v198, v131, v21, v198
	v_fmac_f32_e32 v22, v252, v21
	v_fmac_f32_e32 v198, v252, v197
	v_cvt_pk_bf16_f32 v100, v22, v198
	v_fma_f32 v23, -v131, v198, v23
	v_fma_f32 v199, v131, v22, v199
	v_fmac_f32_e32 v23, v252, v22
	v_fmac_f32_e32 v199, v252, v198
	v_cvt_pk_bf16_f32 v128, v23, v199
	ds_write2_b32 v240, v100, v128 offset0:56 offset1:60
	v_fma_f32 v8, -v131, v199, v8
	v_fma_f32 v40, v131, v23, v40
	v_fmac_f32_e32 v8, v252, v23
	v_fmac_f32_e32 v40, v252, v199
	v_cvt_pk_bf16_f32 v98, v8, v40
	v_fma_f32 v9, -v131, v40, v9
	v_fma_f32 v41, v131, v8, v41
	v_fmac_f32_e32 v9, v252, v8
	v_fmac_f32_e32 v41, v252, v40
	v_cvt_pk_bf16_f32 v99, v9, v41
	ds_write2_b32 v240, v98, v99 offset0:64 offset1:68
	v_fma_f32 v10, -v131, v41, v10
	v_fma_f32 v42, v131, v9, v42
	v_fmac_f32_e32 v10, v252, v9
	v_fmac_f32_e32 v42, v252, v41
	v_cvt_pk_bf16_f32 v100, v10, v42
	v_fma_f32 v11, -v131, v42, v11
	v_fma_f32 v43, v131, v10, v43
	v_fmac_f32_e32 v11, v252, v10
	v_fmac_f32_e32 v43, v252, v42
	v_cvt_pk_bf16_f32 v128, v11, v43
	ds_write2_b32 v240, v100, v128 offset0:72 offset1:76
	v_fma_f32 v24, -v131, v43, v24
	v_fma_f32 v200, v131, v11, v200
	v_fmac_f32_e32 v24, v252, v11
	v_fmac_f32_e32 v200, v252, v43
	v_cvt_pk_bf16_f32 v98, v24, v200
	v_fma_f32 v25, -v131, v200, v25
	v_fma_f32 v201, v131, v24, v201
	v_fmac_f32_e32 v25, v252, v24
	v_fmac_f32_e32 v201, v252, v200
	v_cvt_pk_bf16_f32 v99, v25, v201
	ds_write2_b32 v240, v98, v99 offset0:80 offset1:84
	v_fma_f32 v26, -v131, v201, v26
	v_fma_f32 v202, v131, v25, v202
	v_fmac_f32_e32 v26, v252, v25
	v_fmac_f32_e32 v202, v252, v201
	v_cvt_pk_bf16_f32 v100, v26, v202
	v_fma_f32 v27, -v131, v202, v27
	v_fma_f32 v203, v131, v26, v203
	v_fmac_f32_e32 v27, v252, v26
	v_fmac_f32_e32 v203, v252, v202
	v_cvt_pk_bf16_f32 v128, v27, v203
	ds_write2_b32 v240, v100, v128 offset0:88 offset1:92
	v_fma_f32 v12, -v131, v203, v12
	v_fma_f32 v44, v131, v27, v44
	v_fmac_f32_e32 v12, v252, v27
	v_fmac_f32_e32 v44, v252, v203
	v_cvt_pk_bf16_f32 v98, v12, v44
	v_fma_f32 v13, -v131, v44, v13
	v_fma_f32 v45, v131, v12, v45
	v_fmac_f32_e32 v13, v252, v12
	v_fmac_f32_e32 v45, v252, v44
	v_cvt_pk_bf16_f32 v99, v13, v45
	ds_write2_b32 v240, v98, v99 offset0:96 offset1:100
	v_fma_f32 v14, -v131, v45, v14
	v_fma_f32 v46, v131, v13, v46
	v_fmac_f32_e32 v14, v252, v13
	v_fmac_f32_e32 v46, v252, v45
	v_cvt_pk_bf16_f32 v100, v14, v46
	v_fma_f32 v15, -v131, v46, v15
	v_fma_f32 v47, v131, v14, v47
	v_fmac_f32_e32 v15, v252, v14
	v_fmac_f32_e32 v47, v252, v46
	v_cvt_pk_bf16_f32 v128, v15, v47
	ds_write2_b32 v240, v100, v128 offset0:104 offset1:108
	v_fma_f32 v28, -v131, v47, v28
	v_fma_f32 v204, v131, v15, v204
	v_fmac_f32_e32 v28, v252, v15
	v_fmac_f32_e32 v204, v252, v47
	v_cvt_pk_bf16_f32 v98, v28, v204
	v_fma_f32 v29, -v131, v204, v29
	v_fma_f32 v205, v131, v28, v205
	v_fmac_f32_e32 v29, v252, v28
	v_fmac_f32_e32 v205, v252, v204
	v_cvt_pk_bf16_f32 v99, v29, v205
	ds_write2_b32 v240, v98, v99 offset0:112 offset1:116
	v_fma_f32 v30, -v131, v205, v30
	v_fma_f32 v206, v131, v29, v206
	v_fmac_f32_e32 v30, v252, v29
	v_fmac_f32_e32 v206, v252, v205
	v_cvt_pk_bf16_f32 v100, v30, v206
	v_fma_f32 v174, -v131, v206, v31
	v_fma_f32 v175, v131, v30, v207
	v_fmac_f32_e32 v174, v252, v30
	v_fmac_f32_e32 v175, v252, v206
	v_cvt_pk_bf16_f32 v128, v174, v175
	ds_write2_b32 v240, v100, v128 offset0:120 offset1:124
	ds_read_b128 v[208:211], v241 offset:8192
	ds_read_b128 v[212:215], v241 offset:9248
	ds_read_b128 v[216:219], v241 offset:10304
	ds_read_b128 v[220:223], v241 offset:11360
	ds_read_b128 v[224:227], v241 offset:12416
	ds_read_b128 v[228:231], v241 offset:13472
	ds_read_b128 v[232:235], v241 offset:14528
	ds_read_b128 v[236:239], v241 offset:15584
	s_waitcnt vmcnt(2)
	v_mov_b64_e32 v[48:49], v[52:53]
	v_mov_b64_e32 v[50:51], v[54:55]
	s_cmp_lt_u32 s77, s39
	s_cselect_b32 s46, s48, 0
	s_cselect_b32 s47, s49, 0
	s_add_i32 s77, s77, 1
	v_lshl_add_u64 v[244:245], v[244:245], 0, s[46:47]
	global_load_dwordx4 v[52:55], v[244:245], off
	v_mfma_f32_32x32x16_bf16 v[0:15], v[48:51], v[110:113], 0
	v_mfma_f32_32x32x16_bf16 v[16:31], v[48:51], v[102:105], 0
	v_mfma_f32_32x32x16_bf16 v[32:47], v[48:51], v[106:109], 0
	v_mfma_f32_32x32x16_bf16 v[192:207], v[48:51], v[94:97], 0
	s_waitcnt lgkmcnt(7)
	v_mfma_f32_32x32x16_bf16 v[142:157], v[90:93], v[208:211], 0
	s_nop 6
	v_permlane32_swap_b32 v0, v16
	v_permlane32_swap_b32 v1, v17
	v_permlane32_swap_b32 v2, v18
	v_permlane32_swap_b32 v3, v19
	s_waitcnt lgkmcnt(6)
	v_mfma_f32_32x32x16_bf16 v[158:173], v[86:89], v[212:215], 0
	v_permlane32_swap_b32 v4, v20
	v_permlane32_swap_b32 v5, v21
	v_permlane32_swap_b32 v6, v22
	v_permlane32_swap_b32 v7, v23
	s_waitcnt lgkmcnt(5)
	v_mfma_f32_32x32x16_bf16 v[142:157], v[82:85], v[216:219], v[142:157]
	v_permlane32_swap_b32 v8, v24
	v_permlane32_swap_b32 v9, v25
	v_permlane32_swap_b32 v10, v26
	v_permlane32_swap_b32 v11, v27
	s_waitcnt lgkmcnt(4)
	v_mfma_f32_32x32x16_bf16 v[158:173], v[78:81], v[220:223], v[158:173]
	v_permlane32_swap_b32 v12, v28
	v_permlane32_swap_b32 v13, v29
	v_permlane32_swap_b32 v14, v30
	v_permlane32_swap_b32 v15, v31
	s_waitcnt lgkmcnt(3)
	v_mfma_f32_32x32x16_bf16 v[142:157], v[74:77], v[224:227], v[142:157]
	v_permlane32_swap_b32 v32, v192
	v_permlane32_swap_b32 v33, v193
	v_permlane32_swap_b32 v34, v194
	v_permlane32_swap_b32 v35, v195
	s_waitcnt lgkmcnt(2)
	v_mfma_f32_32x32x16_bf16 v[158:173], v[70:73], v[228:231], v[158:173]
	v_permlane32_swap_b32 v36, v196
	v_permlane32_swap_b32 v37, v197
	v_permlane32_swap_b32 v38, v198
	v_permlane32_swap_b32 v39, v199
	s_waitcnt lgkmcnt(1)
	v_mfma_f32_32x32x16_bf16 v[142:157], v[66:69], v[232:235], v[142:157]
	v_permlane32_swap_b32 v40, v200
	v_permlane32_swap_b32 v41, v201
	v_permlane32_swap_b32 v42, v202
	v_permlane32_swap_b32 v43, v203
	s_waitcnt lgkmcnt(0)
	v_mfma_f32_32x32x16_bf16 v[158:173], v[62:65], v[236:239], v[158:173]
	v_permlane32_swap_b32 v44, v204
	v_permlane32_swap_b32 v45, v205
	v_permlane32_swap_b32 v46, v206
	v_permlane32_swap_b32 v47, v207
	s_add_i32 s76, s76, 1
	s_cmp_lt_u32 s76, s39
	s_cbranch_scc1 .Lscf_loop
	s_nop 15
	v_add_f32_e32 v242, v142, v158
	v_add_f32_e32 v243, v143, v159
	v_add_f32_e32 v60, v144, v160
	v_add_f32_e32 v61, v145, v161
	v_add_f32_e32 v116, v146, v162
	v_add_f32_e32 v117, v147, v163
	v_add_f32_e32 v100, v148, v164
	v_add_f32_e32 v128, v149, v165
	v_cvt_pk_bf16_f32 v242, v242, v243
	v_cvt_pk_bf16_f32 v243, v60, v61
	v_cvt_pk_bf16_f32 v60, v116, v117
	v_cvt_pk_bf16_f32 v61, v100, v128
	global_store_dwordx2 v[246:247], v[242:243], off
	global_store_dwordx2 v[246:247], v[60:61], off offset:16
	v_lshl_add_u64 v[246:247], v[246:247], 0, s[48:49]
	v_mov_b32_e32 v135, v174
	v_mov_b32_e32 v101, v175
	s_branch .LBB0_631
